# P10 scoring: removed 112 redundant v_max canonicalizes; counted vmcnt(11/9/8) at stage end so score stores stay in flight
# speedup vs baseline: 1.0062x; 1.0062x over previous
.LBB0_1094:
	s_and_b32 s44, 1, s33
	s_cselect_b32 s45, 0, 0x9000
	s_cmp_lt_u32 s43, s34
	v_add_u32_e32 v131, s45, v107
	v_lshl_add_u64 v[150:151], s[30:31], 0, v[136:137]
	s_cbranch_scc0 .LBB0_1101
	ds_read_b128 v[0:3], v131
	ds_read_b128 v[16:19], v131 offset:32
	s_add_i32 s45, s43, 1
	s_cmp_ge_u32 s45, s34
	s_waitcnt lgkmcnt(1)
	v_mfma_f32_32x32x16_bf16 v[0:15], v[48:51], v[0:3], 0
	s_waitcnt lgkmcnt(0)
	v_mfma_f32_32x32x16_bf16 v[0:15], v[52:55], v[16:19], v[0:15]
	ds_read_b128 v[16:19], v131 offset:64
	ds_read_b128 v[20:23], v131 offset:4608
	ds_read_b128 v[208:211], v131 offset:4640
	ds_read_b128 v[24:27], v131 offset:9216
	ds_read_b128 v[212:215], v131 offset:9248
	ds_read_b128 v[28:31], v131 offset:96
	ds_read_b128 v[216:219], v131 offset:13824
	ds_read_b128 v[220:223], v131 offset:13856
	ds_read_b128 v[224:227], v131 offset:4672
	ds_read_b128 v[228:231], v131 offset:4704
	ds_read_b128 v[232:235], v131 offset:9280
	ds_read_b128 v[236:239], v131 offset:9312
	ds_read_b128 v[240:243], v131 offset:13888
	ds_read_b128 v[244:247], v131 offset:13920
	s_waitcnt lgkmcnt(13)
	v_mfma_f32_32x32x16_bf16 v[0:15], v[56:59], v[16:19], v[0:15]
	s_waitcnt lgkmcnt(12)
	v_mfma_f32_32x32x16_bf16 v[32:47], v[48:51], v[20:23], 0
	s_waitcnt lgkmcnt(8)
	v_mfma_f32_32x32x16_bf16 v[0:15], v[60:63], v[28:31], v[0:15]
	v_mfma_f32_32x32x16_bf16 v[32:47], v[52:55], v[208:211], v[32:47]
	s_nop 10
	v_max_f32_e32 v4, 0, v4
	v_max_f32_e32 v5, 0, v5
	v_max_f32_e32 v0, 0, v0
	v_max_f32_e32 v12, 0, v12
	v_max_f32_e32 v1, 0, v1
	v_max_f32_e32 v13, 0, v13
	v_pk_mul_f32 v[4:5], v[68:69], v[4:5]
	v_max_f32_e32 v8, 0, v8
	v_max_f32_e32 v9, 0, v9
	v_pk_mul_f32 v[12:13], v[76:77], v[12:13]
	v_pk_fma_f32 v[0:1], v[64:65], v[0:1], v[4:5]
	s_waitcnt lgkmcnt(5)
	v_mfma_f32_32x32x16_bf16 v[32:47], v[56:59], v[224:227], v[32:47]
	v_fma_f32 v4, v72, v8, v12
	v_fma_f32 v5, v73, v9, v13
	v_add_f32_e32 v0, 0, v0
	v_add_f32_e32 v8, v1, v0
	v_add_f32_e32 v0, 0, v4
	v_add_f32_e32 v9, v5, v0
	v_max_f32_e32 v0, v2, v2
	v_max_f32_e32 v2, 0, v6
	v_max_f32_e32 v4, 0, v10
	v_max_f32_e32 v6, 0, v14
	v_max_f32_e32 v1, v3, v3
	v_max_f32_e32 v3, 0, v7
	v_max_f32_e32 v0, 0, v0
	v_max_f32_e32 v1, 0, v1
	v_pk_mul_f32 v[2:3], v[70:71], v[2:3]
	s_waitcnt lgkmcnt(4)
	v_mfma_f32_32x32x16_bf16 v[32:47], v[60:63], v[228:231], v[32:47]
	v_fma_f32 v0, v66, v0, v2
	v_fma_f32 v1, v67, v1, v3
	v_add_f32_e32 v0, v0, v8
	v_add_f32_e32 v133, v1, v0
	v_max_f32_e32 v5, 0, v11
	v_max_f32_e32 v7, 0, v15
	v_pk_mul_f32 v[0:1], v[78:79], v[6:7]
	s_nop 2
	v_pk_fma_f32 v[0:1], v[74:75], v[4:5], v[0:1]
	v_mfma_f32_32x32x16_bf16 v[16:31], v[48:51], v[24:27], 0
	v_add_f32_e32 v0, v0, v9
	v_add_f32_e32 v135, v1, v0
	v_max_f32_e32 v32, 0, v32
	v_max_f32_e32 v36, 0, v36
	v_mul_f32_e32 v36, v68, v36
	v_mfma_f32_32x32x16_bf16 v[0:15], v[48:51], v[216:219], 0
	v_max_f32_e32 v37, 0, v37
	v_fmac_f32_e32 v36, v64, v32
	v_max_f32_e32 v33, 0, v33
	v_mul_f32_e32 v37, v69, v37
	v_add_f32_e32 v32, 0, v36
	v_max_f32_e32 v36, v40, v40
	v_fmac_f32_e32 v37, v65, v33
	v_max_f32_e32 v40, 0, v44
	v_add_f32_e32 v32, v37, v32
	v_max_f32_e32 v36, 0, v36
	v_mul_f32_e32 v40, v76, v40
	v_max_f32_e32 v37, 0, v45
	v_fmac_f32_e32 v40, v72, v36
	v_max_f32_e32 v33, 0, v41
	v_mul_f32_e32 v37, v77, v37
	v_add_f32_e32 v36, 0, v40
	v_fmac_f32_e32 v37, v73, v33
	v_add_f32_e32 v33, v37, v36
	v_mfma_f32_32x32x16_bf16 v[16:31], v[52:55], v[212:215], v[16:31]
	v_max_f32_e32 v36, 0, v38
	v_max_f32_e32 v34, 0, v34
	v_mul_f32_e32 v36, v70, v36
	v_fmac_f32_e32 v36, v66, v34
	v_add_f32_e32 v32, v36, v32
	v_mfma_f32_32x32x16_bf16 v[0:15], v[52:55], v[220:223], v[0:15]
	v_max_f32_e32 v36, 0, v46
	v_max_f32_e32 v34, 0, v42
	v_mul_f32_e32 v36, v78, v36
	v_fmac_f32_e32 v36, v74, v34
	v_add_f32_e32 v34, v36, v33
	v_max_f32_e32 v33, v35, v35
	s_waitcnt lgkmcnt(3)
	v_mfma_f32_32x32x16_bf16 v[16:31], v[56:59], v[232:235], v[16:31]
	v_max_f32_e32 v35, 0, v39
	v_max_f32_e32 v33, 0, v33
	v_mul_f32_e32 v35, v71, v35
	v_fmac_f32_e32 v35, v67, v33
	v_add_f32_e32 v33, v35, v32
	s_waitcnt lgkmcnt(1)
	v_mfma_f32_32x32x16_bf16 v[0:15], v[56:59], v[240:243], v[0:15]
	v_max_f32_e32 v35, 0, v47
	v_max_f32_e32 v32, 0, v43
	v_mul_f32_e32 v35, v79, v35
	v_and_b32_e32 v36, 64, v206
	v_fmac_f32_e32 v35, v75, v32
	v_xor_b32_e32 v32, 32, v206
	v_add_u32_e32 v36, 64, v36
	v_cmp_lt_i32_e32 vcc, v32, v36
	v_mfma_f32_32x32x16_bf16 v[16:31], v[60:63], v[236:239], v[16:31]
	v_cndmask_b32_e64 v208, v133, v135, s[0:1]
	v_cndmask_b32_e32 v32, v206, v32, vcc
	v_lshlrev_b32_e32 v32, 2, v32
	v_add_f32_e32 v34, v35, v34
	ds_bpermute_b32 v36, v32, v208
	v_cndmask_b32_e64 v35, v33, v34, s[0:1]
	ds_bpermute_b32 v35, v32, v35
	s_waitcnt lgkmcnt(2)
	v_mfma_f32_32x32x16_bf16 v[0:15], v[60:63], v[244:247], v[0:15]
	v_cndmask_b32_e64 v37, v135, v133, s[0:1]
	s_waitcnt lgkmcnt(1)
	v_add_f32_e32 v36, v37, v36
	global_store_dword v[150:151], v36, off offset:-512
	s_cbranch_scc1 .LBB0_1097
	v_cndmask_b32_e64 v33, v34, v33, s[0:1]
	s_waitcnt lgkmcnt(0)
	v_add_f32_e32 v33, v33, v35
	global_store_dword v[150:151], v33, off offset:-384
.LBB0_1097:
	v_max_f32_e32 v20, 0, v20
	v_max_f32_e32 v16, 0, v16
	v_mul_f32_e32 v20, v68, v20
	v_max_f32_e32 v21, 0, v21
	v_fmac_f32_e32 v20, v64, v16
	v_max_f32_e32 v17, 0, v17
	v_mul_f32_e32 v21, v69, v21
	v_add_f32_e32 v16, 0, v20
	v_max_f32_e32 v20, v24, v24
	v_fmac_f32_e32 v21, v65, v17
	v_max_f32_e32 v24, 0, v28
	v_add_f32_e32 v16, v21, v16
	v_max_f32_e32 v20, 0, v20
	v_mul_f32_e32 v24, v76, v24
	v_max_f32_e32 v21, 0, v29
	v_fmac_f32_e32 v24, v72, v20
	v_max_f32_e32 v17, 0, v25
	v_mul_f32_e32 v21, v77, v21
	v_add_f32_e32 v20, 0, v24
	v_fmac_f32_e32 v21, v73, v17
	v_add_f32_e32 v17, v21, v20
	v_max_f32_e32 v20, 0, v22
	v_max_f32_e32 v18, 0, v18
	v_mul_f32_e32 v20, v70, v20
	v_fmac_f32_e32 v20, v66, v18
	v_add_f32_e32 v16, v20, v16
	v_max_f32_e32 v20, 0, v30
	v_max_f32_e32 v18, 0, v26
	v_mul_f32_e32 v20, v78, v20
	v_fmac_f32_e32 v20, v74, v18
	v_max_f32_e32 v18, v19, v19
	v_max_f32_e32 v19, 0, v23
	v_max_f32_e32 v18, 0, v18
	v_mul_f32_e32 v19, v71, v19
	v_fmac_f32_e32 v19, v67, v18
	v_add_f32_e32 v16, v19, v16
	v_max_f32_e32 v19, 0, v31
	v_max_f32_e32 v18, 0, v27
	v_mul_f32_e32 v19, v79, v19
	v_add_f32_e32 v17, v20, v17
	v_fmac_f32_e32 v19, v75, v18
	v_add_f32_e32 v17, v19, v17
	v_cndmask_b32_e64 v18, v16, v17, s[0:1]
	ds_bpermute_b32 v18, v32, v18
	s_add_i32 s45, s43, 2
	s_cmp_ge_u32 s45, s34
	s_cbranch_scc1 .LBB0_1099
	v_cndmask_b32_e64 v16, v17, v16, s[0:1]
	s_waitcnt lgkmcnt(0)
	v_add_f32_e32 v16, v16, v18
	global_store_dword v[150:151], v16, off offset:-256
.LBB0_1099:
	v_max_f32_e32 v4, 0, v4
	v_max_f32_e32 v0, 0, v0
	v_mul_f32_e32 v4, v68, v4
	v_max_f32_e32 v5, 0, v5
	v_fmac_f32_e32 v4, v64, v0
	v_max_f32_e32 v1, 0, v1
	v_mul_f32_e32 v5, v69, v5
	v_add_f32_e32 v0, 0, v4
	v_max_f32_e32 v4, v8, v8
	v_fmac_f32_e32 v5, v65, v1
	v_max_f32_e32 v8, 0, v12
	v_add_f32_e32 v0, v5, v0
	v_max_f32_e32 v4, 0, v4
	v_mul_f32_e32 v8, v76, v8
	v_max_f32_e32 v5, 0, v13
	v_fmac_f32_e32 v8, v72, v4
	v_max_f32_e32 v1, 0, v9
	v_mul_f32_e32 v5, v77, v5
	v_add_f32_e32 v4, 0, v8
	v_fmac_f32_e32 v5, v73, v1
	v_add_f32_e32 v1, v5, v4
	v_max_f32_e32 v4, 0, v6
	v_max_f32_e32 v2, 0, v2
	v_mul_f32_e32 v4, v70, v4
	v_fmac_f32_e32 v4, v66, v2
	v_add_f32_e32 v0, v4, v0
	v_max_f32_e32 v4, 0, v14
	v_max_f32_e32 v2, 0, v10
	v_mul_f32_e32 v4, v78, v4
	v_fmac_f32_e32 v4, v74, v2
	v_max_f32_e32 v2, v3, v3
	v_max_f32_e32 v3, 0, v7
	v_max_f32_e32 v2, 0, v2
	v_mul_f32_e32 v3, v71, v3
	v_fmac_f32_e32 v3, v67, v2
	v_add_f32_e32 v0, v3, v0
	v_max_f32_e32 v3, 0, v15
	v_max_f32_e32 v2, 0, v11
	v_mul_f32_e32 v3, v79, v3
	v_add_f32_e32 v1, v4, v1
	v_fmac_f32_e32 v3, v75, v2
	v_add_f32_e32 v1, v3, v1
	v_cndmask_b32_e64 v2, v0, v1, s[0:1]
	ds_bpermute_b32 v2, v32, v2
	s_add_i32 s45, s43, 3
	s_cmp_ge_u32 s45, s34
	s_cbranch_scc1 .LBB0_1101
	v_cndmask_b32_e64 v0, v1, v0, s[0:1]
	s_waitcnt lgkmcnt(0)
	v_add_f32_e32 v0, v0, v2
	global_store_dword v[150:151], v0, off offset:-128
.LBB0_1101:
	s_add_i32 s45, s43, 4
	s_cmp_ge_u32 s45, s34
	s_cbranch_scc1 .LBB0_1108
	s_waitcnt lgkmcnt(0)
	ds_read_b128 v[0:3], v131 offset:18432
	ds_read_b128 v[16:19], v131 offset:18464
	s_add_i32 s45, s43, 5
	s_cmp_ge_u32 s45, s34
	s_waitcnt lgkmcnt(1)
	v_mfma_f32_32x32x16_bf16 v[0:15], v[48:51], v[0:3], 0
	s_waitcnt lgkmcnt(0)
	v_mfma_f32_32x32x16_bf16 v[0:15], v[52:55], v[16:19], v[0:15]
	ds_read_b128 v[16:19], v131 offset:18496
	ds_read_b128 v[20:23], v131 offset:23040
	ds_read_b128 v[208:211], v131 offset:23072
	ds_read_b128 v[24:27], v131 offset:27648
	ds_read_b128 v[212:215], v131 offset:27680
	ds_read_b128 v[28:31], v131 offset:18528
	ds_read_b128 v[216:219], v131 offset:32256
	ds_read_b128 v[220:223], v131 offset:32288
	ds_read_b128 v[224:227], v131 offset:23104
	ds_read_b128 v[228:231], v131 offset:23136
	ds_read_b128 v[232:235], v131 offset:27712
	ds_read_b128 v[236:239], v131 offset:27744
	ds_read_b128 v[240:243], v131 offset:32320
	ds_read_b128 v[244:247], v131 offset:32352
	s_waitcnt lgkmcnt(13)
	v_mfma_f32_32x32x16_bf16 v[0:15], v[56:59], v[16:19], v[0:15]
	s_waitcnt lgkmcnt(12)
	v_mfma_f32_32x32x16_bf16 v[32:47], v[48:51], v[20:23], 0
	s_waitcnt lgkmcnt(8)
	v_mfma_f32_32x32x16_bf16 v[0:15], v[60:63], v[28:31], v[0:15]
	v_mfma_f32_32x32x16_bf16 v[32:47], v[52:55], v[208:211], v[32:47]
	s_nop 10
	v_max_f32_e32 v4, 0, v4
	v_max_f32_e32 v5, 0, v5
	v_max_f32_e32 v0, 0, v0
	v_max_f32_e32 v12, 0, v12
	v_max_f32_e32 v1, 0, v1
	v_max_f32_e32 v13, 0, v13
	v_pk_mul_f32 v[4:5], v[68:69], v[4:5]
	v_max_f32_e32 v8, 0, v8
	v_max_f32_e32 v9, 0, v9
	v_pk_mul_f32 v[12:13], v[76:77], v[12:13]
	v_pk_fma_f32 v[0:1], v[64:65], v[0:1], v[4:5]
	s_waitcnt lgkmcnt(5)
	v_mfma_f32_32x32x16_bf16 v[32:47], v[56:59], v[224:227], v[32:47]
	v_fma_f32 v4, v72, v8, v12
	v_fma_f32 v5, v73, v9, v13
	v_add_f32_e32 v0, 0, v0
	v_add_f32_e32 v8, v1, v0
	v_add_f32_e32 v0, 0, v4
	v_add_f32_e32 v9, v5, v0
	v_max_f32_e32 v0, v2, v2
	v_max_f32_e32 v2, 0, v6
	v_max_f32_e32 v4, 0, v10
	v_max_f32_e32 v6, 0, v14
	v_max_f32_e32 v1, v3, v3
	v_max_f32_e32 v3, 0, v7
	v_max_f32_e32 v0, 0, v0
	v_max_f32_e32 v1, 0, v1
	v_pk_mul_f32 v[2:3], v[70:71], v[2:3]
	s_waitcnt lgkmcnt(4)
	v_mfma_f32_32x32x16_bf16 v[32:47], v[60:63], v[228:231], v[32:47]
	v_fma_f32 v0, v66, v0, v2
	v_fma_f32 v1, v67, v1, v3
	v_add_f32_e32 v0, v0, v8
	v_add_f32_e32 v131, v1, v0
	v_max_f32_e32 v5, 0, v11
	v_max_f32_e32 v7, 0, v15
	v_pk_mul_f32 v[0:1], v[78:79], v[6:7]
	s_nop 2
	v_pk_fma_f32 v[0:1], v[74:75], v[4:5], v[0:1]
	v_mfma_f32_32x32x16_bf16 v[16:31], v[48:51], v[24:27], 0
	v_add_f32_e32 v0, v0, v9
	v_add_f32_e32 v133, v1, v0
	v_max_f32_e32 v32, 0, v32
	v_max_f32_e32 v36, 0, v36
	v_mul_f32_e32 v36, v68, v36
	v_mfma_f32_32x32x16_bf16 v[0:15], v[48:51], v[216:219], 0
	v_max_f32_e32 v37, 0, v37
	v_fmac_f32_e32 v36, v64, v32
	v_max_f32_e32 v33, 0, v33
	v_mul_f32_e32 v37, v69, v37
	v_add_f32_e32 v32, 0, v36
	v_max_f32_e32 v36, v40, v40
	v_fmac_f32_e32 v37, v65, v33
	v_max_f32_e32 v40, 0, v44
	v_add_f32_e32 v32, v37, v32
	v_max_f32_e32 v36, 0, v36
	v_mul_f32_e32 v40, v76, v40
	v_max_f32_e32 v37, 0, v45
	v_fmac_f32_e32 v40, v72, v36
	v_max_f32_e32 v33, 0, v41
	v_mul_f32_e32 v37, v77, v37
	v_add_f32_e32 v36, 0, v40
	v_fmac_f32_e32 v37, v73, v33
	v_add_f32_e32 v33, v37, v36
	v_mfma_f32_32x32x16_bf16 v[16:31], v[52:55], v[212:215], v[16:31]
	v_max_f32_e32 v36, 0, v38
	v_max_f32_e32 v34, 0, v34
	v_mul_f32_e32 v36, v70, v36
	v_fmac_f32_e32 v36, v66, v34
	v_add_f32_e32 v32, v36, v32
	v_mfma_f32_32x32x16_bf16 v[0:15], v[52:55], v[220:223], v[0:15]
	v_max_f32_e32 v36, 0, v46
	v_max_f32_e32 v34, 0, v42
	v_mul_f32_e32 v36, v78, v36
	v_fmac_f32_e32 v36, v74, v34
	v_add_f32_e32 v34, v36, v33
	v_max_f32_e32 v33, v35, v35
	s_waitcnt lgkmcnt(3)
	v_mfma_f32_32x32x16_bf16 v[16:31], v[56:59], v[232:235], v[16:31]
	v_max_f32_e32 v35, 0, v39
	v_max_f32_e32 v33, 0, v33
	v_mul_f32_e32 v35, v71, v35
	v_fmac_f32_e32 v35, v67, v33
	v_add_f32_e32 v33, v35, v32
	s_waitcnt lgkmcnt(1)
	v_mfma_f32_32x32x16_bf16 v[0:15], v[56:59], v[240:243], v[0:15]
	v_max_f32_e32 v35, 0, v47
	v_max_f32_e32 v32, 0, v43
	v_mul_f32_e32 v35, v79, v35
	v_and_b32_e32 v36, 64, v206
	v_fmac_f32_e32 v35, v75, v32
	v_xor_b32_e32 v32, 32, v206
	v_add_u32_e32 v36, 64, v36
	v_cmp_lt_i32_e32 vcc, v32, v36
	v_mfma_f32_32x32x16_bf16 v[16:31], v[60:63], v[236:239], v[16:31]
	v_cndmask_b32_e64 v135, v131, v133, s[0:1]
	v_cndmask_b32_e32 v32, v206, v32, vcc
	v_lshlrev_b32_e32 v32, 2, v32
	v_add_f32_e32 v34, v35, v34
	ds_bpermute_b32 v36, v32, v135
	v_cndmask_b32_e64 v35, v33, v34, s[0:1]
	ds_bpermute_b32 v35, v32, v35
	s_waitcnt lgkmcnt(2)
	v_mfma_f32_32x32x16_bf16 v[0:15], v[60:63], v[244:247], v[0:15]
	v_cndmask_b32_e64 v37, v133, v131, s[0:1]
	s_waitcnt lgkmcnt(1)
	v_add_f32_e32 v36, v37, v36
	global_store_dword v[150:151], v36, off
	s_cbranch_scc1 .LBB0_1104
	v_cndmask_b32_e64 v33, v34, v33, s[0:1]
	s_waitcnt lgkmcnt(0)
	v_add_f32_e32 v33, v33, v35
	global_store_dword v[150:151], v33, off offset:128
.LBB0_1104:
	v_max_f32_e32 v20, 0, v20
	v_max_f32_e32 v16, 0, v16
	v_mul_f32_e32 v20, v68, v20
	v_max_f32_e32 v21, 0, v21
	v_fmac_f32_e32 v20, v64, v16
	v_max_f32_e32 v17, 0, v17
	v_mul_f32_e32 v21, v69, v21
	v_add_f32_e32 v16, 0, v20
	v_max_f32_e32 v20, v24, v24
	v_fmac_f32_e32 v21, v65, v17
	v_max_f32_e32 v24, 0, v28
	v_add_f32_e32 v16, v21, v16
	v_max_f32_e32 v20, 0, v20
	v_mul_f32_e32 v24, v76, v24
	v_max_f32_e32 v21, 0, v29
	v_fmac_f32_e32 v24, v72, v20
	v_max_f32_e32 v17, 0, v25
	v_mul_f32_e32 v21, v77, v21
	v_add_f32_e32 v20, 0, v24
	v_fmac_f32_e32 v21, v73, v17
	v_add_f32_e32 v17, v21, v20
	v_max_f32_e32 v20, 0, v22
	v_max_f32_e32 v18, 0, v18
	v_mul_f32_e32 v20, v70, v20
	v_fmac_f32_e32 v20, v66, v18
	v_add_f32_e32 v16, v20, v16
	v_max_f32_e32 v20, 0, v30
	v_max_f32_e32 v18, 0, v26
	v_mul_f32_e32 v20, v78, v20
	v_fmac_f32_e32 v20, v74, v18
	v_max_f32_e32 v18, v19, v19
	v_max_f32_e32 v19, 0, v23
	v_max_f32_e32 v18, 0, v18
	v_mul_f32_e32 v19, v71, v19
	v_fmac_f32_e32 v19, v67, v18
	v_add_f32_e32 v16, v19, v16
	v_max_f32_e32 v19, 0, v31
	v_max_f32_e32 v18, 0, v27
	v_mul_f32_e32 v19, v79, v19
	v_add_f32_e32 v17, v20, v17
	v_fmac_f32_e32 v19, v75, v18
	v_add_f32_e32 v17, v19, v17
	v_cndmask_b32_e64 v18, v16, v17, s[0:1]
	ds_bpermute_b32 v18, v32, v18
	s_add_i32 s45, s43, 6
	s_cmp_ge_u32 s45, s34
	s_cbranch_scc1 .LBB0_1106
	v_cndmask_b32_e64 v16, v17, v16, s[0:1]
	s_waitcnt lgkmcnt(0)
	v_add_f32_e32 v16, v16, v18
	global_store_dword v[150:151], v16, off offset:256
.LBB0_1106:
	v_max_f32_e32 v4, 0, v4
	v_max_f32_e32 v0, 0, v0
	v_mul_f32_e32 v4, v68, v4
	v_max_f32_e32 v5, 0, v5
	v_fmac_f32_e32 v4, v64, v0
	v_max_f32_e32 v1, 0, v1
	v_mul_f32_e32 v5, v69, v5
	v_add_f32_e32 v0, 0, v4
	v_max_f32_e32 v4, v8, v8
	v_fmac_f32_e32 v5, v65, v1
	v_max_f32_e32 v8, 0, v12
	v_add_f32_e32 v0, v5, v0
	v_max_f32_e32 v4, 0, v4
	v_mul_f32_e32 v8, v76, v8
	v_max_f32_e32 v5, 0, v13
	v_fmac_f32_e32 v8, v72, v4
	v_max_f32_e32 v1, 0, v9
	v_mul_f32_e32 v5, v77, v5
	v_add_f32_e32 v4, 0, v8
	v_fmac_f32_e32 v5, v73, v1
	v_add_f32_e32 v1, v5, v4
	v_max_f32_e32 v4, 0, v6
	v_max_f32_e32 v2, 0, v2
	v_mul_f32_e32 v4, v70, v4
	v_fmac_f32_e32 v4, v66, v2
	v_add_f32_e32 v0, v4, v0
	v_max_f32_e32 v4, 0, v14
	v_max_f32_e32 v2, 0, v10
	v_mul_f32_e32 v4, v78, v4
	v_fmac_f32_e32 v4, v74, v2
	v_max_f32_e32 v2, v3, v3
	v_max_f32_e32 v3, 0, v7
	v_max_f32_e32 v2, 0, v2
	v_mul_f32_e32 v3, v71, v3
	v_fmac_f32_e32 v3, v67, v2
	v_add_f32_e32 v0, v3, v0
	v_max_f32_e32 v3, 0, v15
	v_max_f32_e32 v2, 0, v11
	v_mul_f32_e32 v3, v79, v3
	v_add_f32_e32 v1, v4, v1
	v_fmac_f32_e32 v3, v75, v2
	v_add_f32_e32 v1, v3, v1
	v_cndmask_b32_e64 v2, v0, v1, s[0:1]
	ds_bpermute_b32 v2, v32, v2
	s_add_i32 s45, s43, 7
	s_cmp_ge_u32 s45, s34
	s_cbranch_scc1 .LBB0_1108
	v_cndmask_b32_e64 v0, v1, v0, s[0:1]
	s_waitcnt lgkmcnt(0)
	v_add_f32_e32 v0, v0, v2
	global_store_dword v[150:151], v0, off offset:384
.LBB0_1108:
	s_and_b64 vcc, exec, s[18:19]
	s_cbranch_vccz .LBB0_1091
	s_cmp_eq_u32 s44, 1
	s_cselect_b32 s18, 0x9000, 0
	v_add_u32_e32 v0, s18, v99
	s_waitcnt lgkmcnt(0)
	v_add_u32_e32 v2, v0, v113
	v_add_u32_e32 v1, v0, v149
	v_add_u32_e32 v0, v0, v147
	s_waitcnt vmcnt(11)
	ds_write_b128 v2, v[80:83]
	s_waitcnt vmcnt(9)
	ds_write_b128 v0, v[84:87]
	ds_write_b128 v2, v[88:91] offset:18432
	s_waitcnt vmcnt(8)
	ds_write_b128 v1, v[92:95]
	s_branch .LBB0_1091
